# P4 attention: gathered first task (loop 790) also software-pipelined fully unrolled 8-step body, both gathered loops pipelined
# speedup vs baseline: 1.0053x; 1.0053x over previous
; DI void attn_task(const Params& P, int bh, int n, int t, int lane, const char* Ks, const char* Vs) {
;     ...
;   const int b = bh >> 3, h = bh & 7, r = lane & 31, hh = lane >> 5;
;   const bool own = t < 8;
;   int lq, slot; bool valid = true;
;   if (own) { lq = n * 256 + t * 32 + r; slot = 3; }
;   else {
;     const int cnt = gcount[bh * 32 + n], idx = (t - 8) * 32 + r;
;     valid = idx < cnt;
;     const int e = list[((long)(bh * 32 + n)) * 8192 + (valid ? idx : 0)];
;     lq = e >> 2; slot = e & 3;
;   }
;   bf16x8 qf[4];
;   {
;     const u16* qrow = Qb + ((long)(b * 8192 + lq)) * 512 + h * 64 + 8 * hh;
; #pragma unroll
;     for (int s = 0; s < 4; ++s) qf[s] = *reinterpret_cast<const bf16x8*>(qrow + 16 * s);
;   }
;   float m_run = -1e30f, l_run = 0.f;
;   f32x16 O0, O1;
; #pragma unroll
;   for (int i = 0; i < 16; ++i) { O0[i] = 0.f; O1[i] = 0.f; }
;   const int nkt = own ? (t + 1) : 8;
;   for (int kt = 0; kt < nkt; ++kt) {
;     const int kbase = n * 256 + kt * 32;
;     const int krow = kt * 32 + r;
;     f32x16 S;
; #pragma unroll
;     for (int i = 0; i < 16; ++i) S[i] = 0.f;
.LBB0_787:
	s_andn2_saveexec_b64 s[0:1], s[0:1]
	v_lshl_add_u32 v0, v0, 5, v145
	v_or_b32_e32 v78, v0, v97
	v_mov_b64_e32 v[70:71], 3
	s_or_b64 s[50:51], s[50:51], exec
	s_or_b64 exec, exec, s[0:1]
	v_lshlrev_b32_e32 v0, 10, v74
	v_and_b32_e32 v0, 0xffffe000, v0
	v_add_u32_e32 v72, v78, v0
	v_ashrrev_i32_e32 v73, 31, v72
	v_bfe_u32 v79, v66, 5, 3
	v_lshlrev_b64 v[2:3], 10, v[72:73]
	v_lshl_add_u64 v[2:3], s[78:79], 0, v[2:3]
	v_lshlrev_b32_e32 v0, 7, v79
	v_lshl_add_u64 v[2:3], v[2:3], 0, v[0:1]
	v_lshlrev_b32_e32 v0, 1, v84
	v_lshl_add_u64 v[2:3], v[2:3], 0, v[0:1]
	global_load_dwordx4 v[50:53], v[2:3], off
	global_load_dwordx4 v[54:57], v[2:3], off offset:32
	global_load_dwordx4 v[58:61], v[2:3], off offset:64
	global_load_dwordx4 v[62:65], v[2:3], off offset:96
	v_lshl_or_b32 v0, v144, 3, v135
	v_lshlrev_b32_e32 v2, 3, v146
	v_mov_b32_e32 v14, v1
	v_mov_b32_e32 v15, v1
	v_sub_u32_e32 v88, v0, v2
	v_mov_b32_e32 v0, v1
	v_mov_b32_e32 v2, v1
	v_mov_b32_e32 v3, v1
	v_mov_b32_e32 v4, v1
	v_mov_b32_e32 v5, v1
	v_mov_b32_e32 v6, v1
	v_mov_b32_e32 v7, v1
	v_mov_b32_e32 v8, v1
	v_mov_b32_e32 v9, v1
	v_mov_b32_e32 v10, v1
	v_mov_b32_e32 v11, v1
	v_mov_b32_e32 v12, v1
	v_mov_b32_e32 v13, v1
	v_mov_b64_e32 v[32:33], v[14:15]
	v_mov_b64_e32 v[30:31], v[12:13]
	v_mov_b64_e32 v[28:29], v[10:11]
	v_mov_b64_e32 v[26:27], v[8:9]
	v_mov_b64_e32 v[24:25], v[6:7]
	v_mov_b64_e32 v[22:23], v[4:5]
	v_mov_b64_e32 v[20:21], v[2:3]
	v_mov_b64_e32 v[18:19], v[0:1]
	v_mov_b64_e32 v[16:17], v[14:15]
	v_add_u32_e32 v89, v99, v145
	s_mov_b32 s8, 0
	v_mov_b32_e32 v151, 0
	v_mov_b32_e32 v71, 0xf149f2ca
	v_mov_b32_e32 v90, v139
	v_mov_b32_e32 v91, v138
	v_mov_b32_e32 v147, v137
	v_mov_b32_e32 v148, v136
	v_mov_b32_e32 v149, v134
	v_mov_b32_e32 v150, v85
	v_mov_b64_e32 v[14:15], v[12:13]
	v_mov_b64_e32 v[12:13], v[10:11]
	v_mov_b64_e32 v[10:11], v[8:9]
	v_mov_b64_e32 v[8:9], v[6:7]
	v_mov_b64_e32 v[6:7], v[4:5]
	v_mov_b64_e32 v[4:5], v[2:3]
	v_mov_b64_e32 v[2:3], v[0:1]
	v_cmp_gt_u32_e32 vcc, 8, v88
	s_cbranch_vccnz .LBB0_790
	s_branch .Lattn_pipe_790

; DI float xor32_max(float v) { const auto r = __builtin_amdgcn_permlane32_swap(__float_as_uint(v), __float_as_uint(v), false, false); return fmaxf(__uint_as_float(r[0]), __uint_as_float(r[1])); }
; DI float xor32_sum(float v) { const auto r = __builtin_amdgcn_permlane32_swap(__float_as_uint(v), __float_as_uint(v), false, false); return __uint_as_float(r[0]) + __uint_as_float(r[1]); }
; DI int crow(int i, int hh) { return (i & 3) + 8 * (i >> 2) + 4 * hh; }
; DI void attn_task(const Params& P, int bh, int n, int t, int lane, const char* Ks, const char* Vs) {
;     ...
;   for (int kt = 0; kt < nkt; ++kt) {
;     const int kbase = n * 256 + kt * 32;
;     const int krow = kt * 32 + r;
;     f32x16 S;
; #pragma unroll
;     for (int i = 0; i < 16; ++i) S[i] = 0.f;
; #pragma unroll
;     for (int s = 0; s < 4; ++s) {
;       const bf16x8 kf = *reinterpret_cast<const bf16x8*>(Ks + krow * 128 + (((2 * s + hh) ^ ((krow >> 1) & 7)) * 16));
;       S = __builtin_amdgcn_mfma_f32_32x32x16_bf16(kf, qf[s], S, 0, 0, 0);
;     }
;     const bool diag = own && (kt == t);
;     constexpr float SC2 = 0.125f * 1.4426950408889634f;
;     float mx = -1e30f;
; #pragma unroll
;     for (int i = 0; i < 16; ++i) {
;       if (diag && (kbase + crow(i, hh) > lq)) S[i] = -1e30f;
;       mx = fmaxf(mx, S[i]);
;     }
;     mx = xor32_max(mx);
;     const float m_new = fmaxf(m_run, mx * SC2);
;     const float alpha = __builtin_amdgcn_exp2f(m_run - m_new);
;     float rs = 0.f;
; #pragma unroll
;     for (int i = 0; i < 16; ++i) { float pv = __builtin_amdgcn_exp2f(fmaf(S[i], SC2, -m_new)); S[i] = pv; rs += pv; }
;     rs = xor32_sum(rs);
;     l_run = l_run * alpha + rs; m_run = m_new;
;     if (__ballot(alpha != 1.f)) {
; #pragma unroll
;       for (int i = 0; i < 16; ++i) { O0[i] *= alpha; O1[i] *= alpha; }
;     }
.Lattn_pipe_790:
	v_add_u32_e32 v248, v148, v197
	v_add_u32_e32 v249, v147, v197
	v_add_u32_e32 v250, v91, v197
	v_add_u32_e32 v251, v90, v197
	v_add_u32_e32 v210, v149, v197
	v_add_u32_e32 v211, v150, v197
	ds_read_b128 v[176:179], v248 offset:0
	ds_read_b128 v[180:183], v249 offset:0
	ds_read_b128 v[184:187], v250 offset:0
	ds_read_b128 v[200:203], v251 offset:0
	s_waitcnt vmcnt(0) lgkmcnt(0)
	v_mfma_f32_32x32x16_bf16 v[34:49], v[176:179], v[50:53], 0
	v_mfma_f32_32x32x16_bf16 v[34:49], v[180:183], v[54:57], v[34:49]
	v_mfma_f32_32x32x16_bf16 v[34:49], v[184:187], v[58:61], v[34:49]
	v_mfma_f32_32x32x16_bf16 v[34:49], v[200:203], v[62:65], v[34:49]
	ds_read_b128 v[176:179], v248 offset:4096
	ds_read_b128 v[180:183], v249 offset:4096
	ds_read_b128 v[184:187], v250 offset:4096
	ds_read_b128 v[200:203], v251 offset:4096
	s_nop 7
	s_waitcnt lgkmcnt(0)
	v_mfma_f32_32x32x16_bf16 v[232:247], v[176:179], v[50:53], 0
	ds_read2_b64 v[216:219], v210 offset0:0 offset1:2
	ds_read2_b64 v[220:223], v211 offset0:0 offset1:2
	ds_read2_b64 v[224:227], v210 offset0:4 offset1:6
	ds_read2_b64 v[228:231], v211 offset0:4 offset1:6
	v_max3_f32 v152, v34, s22, v35
	v_max3_f32 v152, v152, v36, v37
	v_max3_f32 v152, v152, v38, v39
	v_max3_f32 v152, v152, v40, v41
	v_max3_f32 v152, v152, v42, v43
	v_max3_f32 v152, v152, v44, v45
	v_max3_f32 v152, v152, v46, v47
	v_max3_f32 v152, v152, v48, v49
	v_mfma_f32_32x32x16_bf16 v[232:247], v[180:183], v[54:57], v[232:247]
	v_mov_b32_e32 v153, v152
	s_nop 1
	v_permlane32_swap_b32_e32 v152, v153
	v_max_f32_e32 v152, v152, v153
	v_mul_f32_e32 v152, 0x3e38aa3b, v152
	v_max_f32_e32 v154, v71, v152
	v_sub_f32_e32 v0, v71, v154
	v_pk_fma_f32 v[34:35], v[34:35], s[22:23], v[154:155] op_sel:[0,1,0] op_sel_hi:[1,1,0] neg_lo:[0,0,1] neg_hi:[0,0,1]
	v_pk_fma_f32 v[36:37], v[36:37], s[22:23], v[154:155] op_sel:[0,1,0] op_sel_hi:[1,1,0] neg_lo:[0,0,1] neg_hi:[0,0,1]
	v_pk_fma_f32 v[38:39], v[38:39], s[22:23], v[154:155] op_sel:[0,1,0] op_sel_hi:[1,1,0] neg_lo:[0,0,1] neg_hi:[0,0,1]
	v_pk_fma_f32 v[40:41], v[40:41], s[22:23], v[154:155] op_sel:[0,1,0] op_sel_hi:[1,1,0] neg_lo:[0,0,1] neg_hi:[0,0,1]
	v_pk_fma_f32 v[42:43], v[42:43], s[22:23], v[154:155] op_sel:[0,1,0] op_sel_hi:[1,1,0] neg_lo:[0,0,1] neg_hi:[0,0,1]
	v_pk_fma_f32 v[44:45], v[44:45], s[22:23], v[154:155] op_sel:[0,1,0] op_sel_hi:[1,1,0] neg_lo:[0,0,1] neg_hi:[0,0,1]
	v_pk_fma_f32 v[46:47], v[46:47], s[22:23], v[154:155] op_sel:[0,1,0] op_sel_hi:[1,1,0] neg_lo:[0,0,1] neg_hi:[0,0,1]
	v_pk_fma_f32 v[48:49], v[48:49], s[22:23], v[154:155] op_sel:[0,1,0] op_sel_hi:[1,1,0] neg_lo:[0,0,1] neg_hi:[0,0,1]
	v_mfma_f32_32x32x16_bf16 v[232:247], v[184:187], v[58:61], v[232:247]
	v_exp_f32_e32 v0, v0
	v_exp_f32_e32 v34, v34
	v_exp_f32_e32 v35, v35
	v_exp_f32_e32 v36, v36
	v_exp_f32_e32 v37, v37
	v_exp_f32_e32 v38, v38
	v_exp_f32_e32 v39, v39
	v_exp_f32_e32 v40, v40
	v_mfma_f32_32x32x16_bf16 v[232:247], v[200:203], v[62:65], v[232:247]
	ds_read_b128 v[176:179], v248 offset:8192
	ds_read_b128 v[180:183], v249 offset:8192
	ds_read_b128 v[184:187], v250 offset:8192
	ds_read_b128 v[200:203], v251 offset:8192
	v_exp_f32_e32 v41, v41
	v_exp_f32_e32 v42, v42
	v_exp_f32_e32 v43, v43
	v_exp_f32_e32 v44, v44
	v_exp_f32_e32 v45, v45
	v_exp_f32_e32 v46, v46
	v_exp_f32_e32 v47, v47
	v_exp_f32_e32 v48, v48
	v_exp_f32_e32 v49, v49
	v_mov_b32_e32 v71, v154
	v_pk_add_f32 v[156:157], v[34:35], v[36:37]
	v_pk_add_f32 v[158:159], v[38:39], v[40:41]
	v_pk_add_f32 v[160:161], v[42:43], v[44:45]
	v_pk_add_f32 v[204:205], v[46:47], v[48:49]
	v_pk_add_f32 v[156:157], v[156:157], v[158:159]
	v_pk_add_f32 v[160:161], v[160:161], v[204:205]
	v_pk_add_f32 v[156:157], v[156:157], v[160:161]
	v_add_f32_e32 v206, v156, v157
	v_mov_b32_e32 v207, v206
	s_nop 1
	v_permlane32_swap_b32_e32 v206, v207
	v_cmp_neq_f32_e32 vcc, 1.0, v0
	s_cbranch_vccz .Lattn_qkeep_0
	v_pk_mul_f32 v[32:33], v[32:33], v[0:1] op_sel_hi:[1,0]
	v_pk_mul_f32 v[30:31], v[30:31], v[0:1] op_sel_hi:[1,0]
	v_pk_mul_f32 v[28:29], v[28:29], v[0:1] op_sel_hi:[1,0]
	v_pk_mul_f32 v[26:27], v[26:27], v[0:1] op_sel_hi:[1,0]
	v_pk_mul_f32 v[24:25], v[24:25], v[0:1] op_sel_hi:[1,0]
	v_pk_mul_f32 v[22:23], v[22:23], v[0:1] op_sel_hi:[1,0]
	v_pk_mul_f32 v[20:21], v[20:21], v[0:1] op_sel_hi:[1,0]
	v_pk_mul_f32 v[18:19], v[18:19], v[0:1] op_sel_hi:[1,0]
	v_pk_mul_f32 v[16:17], v[16:17], v[0:1] op_sel_hi:[1,0]
	v_pk_mul_f32 v[14:15], v[14:15], v[0:1] op_sel_hi:[1,0]
	v_pk_mul_f32 v[12:13], v[12:13], v[0:1] op_sel_hi:[1,0]
	v_pk_mul_f32 v[10:11], v[10:11], v[0:1] op_sel_hi:[1,0]
	v_pk_mul_f32 v[8:9], v[8:9], v[0:1] op_sel_hi:[1,0]
	v_pk_mul_f32 v[6:7], v[6:7], v[0:1] op_sel_hi:[1,0]
	v_pk_mul_f32 v[4:5], v[4:5], v[0:1] op_sel_hi:[1,0]
	v_pk_mul_f32 v[2:3], v[2:3], v[0:1] op_sel_hi:[1,0]
; DI unsigned pack2bf(float a, float b) { const f2_t v = {a, b}; return __builtin_bit_cast(unsigned, __builtin_convertvector(v, bf2_t)); }
; DI float xor32_max(float v) { const auto r = __builtin_amdgcn_permlane32_swap(__float_as_uint(v), __float_as_uint(v), false, false); return fmaxf(__uint_as_float(r[0]), __uint_as_float(r[1])); }
; DI int crow(int i, int hh) { return (i & 3) + 8 * (i >> 2) + 4 * hh; }
; DI void attn_task(const Params& P, int bh, int n, int t, int lane, const char* Ks, const char* Vs) {
;     ...
;     for (int s = 0; s < 4; ++s) {
;       const bf16x8 kf = *reinterpret_cast<const bf16x8*>(Ks + krow * 128 + (((2 * s + hh) ^ ((krow >> 1) & 7)) * 16));
;       S = __builtin_amdgcn_mfma_f32_32x32x16_bf16(kf, qf[s], S, 0, 0, 0);
;     }
;     const bool diag = own && (kt == t);
;     constexpr float SC2 = 0.125f * 1.4426950408889634f;
;     float mx = -1e30f;
; #pragma unroll
;     for (int i = 0; i < 16; ++i) {
;       if (diag && (kbase + crow(i, hh) > lq)) S[i] = -1e30f;
;       mx = fmaxf(mx, S[i]);
;     }
;     mx = xor32_max(mx);
;     const float m_new = fmaxf(m_run, mx * SC2);
;     const float alpha = __builtin_amdgcn_exp2f(m_run - m_new);
;     float rs = 0.f;
; #pragma unroll
;     for (int i = 0; i < 16; ++i) { float pv = __builtin_amdgcn_exp2f(fmaf(S[i], SC2, -m_new)); S[i] = pv; rs += pv; }
;     rs = xor32_sum(rs);
;     l_run = l_run * alpha + rs; m_run = m_new;
;     if (__ballot(alpha != 1.f)) {
; #pragma unroll
;       for (int i = 0; i < 16; ++i) { O0[i] *= alpha; O1[i] *= alpha; }
;     }
; #pragma unroll
;     for (int s = 0; s < 2; ++s) {
;       const uint4 ppk = make_uint4(pack2bf(S[8 * s], S[8 * s + 1]), pack2bf(S[8 * s + 2], S[8 * s + 3]), pack2bf(S[8 * s + 4], S[8 * s + 5]), pack2bf(S[8 * s + 6], S[8 * s + 7]));
;       const bf16x8 pf = __builtin_bit_cast(bf16x8, ppk);
; #pragma unroll
;       for (int dt = 0; dt < 2; ++dt) {
;         const char* vp = Vs + (dt * 32 + r) * 528 + (kt * 32 + 16 * s + 4 * hh) * 2;
;         const uint2 lo = *reinterpret_cast<const uint2*>(vp), hi = *reinterpret_cast<const uint2*>(vp + 16);
;         const uint4 vv = make_uint4(lo.x, lo.y, hi.x, hi.y);
;         if (dt == 0) O0 = __builtin_amdgcn_mfma_f32_32x32x16_bf16(__builtin_bit_cast(bf16x8, vv), pf, O0, 0, 0, 0);
;         else O1 = __builtin_amdgcn_mfma_f32_32x32x16_bf16(__builtin_bit_cast(bf16x8, vv), pf, O1, 0, 0, 0);
;       }
.Lattn_qkeep_0:
	v_add_f32_e32 v252, v206, v207
	v_fmac_f32_e32 v252, v151, v0
	v_cvt_pk_bf16_f32 v156, v34, v35
	v_cvt_pk_bf16_f32 v157, v36, v37
	v_cvt_pk_bf16_f32 v158, v38, v39
	v_cvt_pk_bf16_f32 v159, v40, v41
	v_cvt_pk_bf16_f32 v152, v42, v43
	v_cvt_pk_bf16_f32 v153, v44, v45
	v_cvt_pk_bf16_f32 v154, v46, v47
	v_cvt_pk_bf16_f32 v155, v48, v49
	v_mov_b32_e32 v151, v252
	s_waitcnt lgkmcnt(0)
	v_mfma_f32_32x32x16_bf16 v[18:33], v[216:219], v[156:159], v[18:33]
	v_mfma_f32_32x32x16_bf16 v[2:17], v[220:223], v[156:159], v[2:17]
	v_mfma_f32_32x32x16_bf16 v[18:33], v[224:227], v[152:155], v[18:33]
	v_mfma_f32_32x32x16_bf16 v[2:17], v[228:231], v[152:155], v[2:17]
	s_waitcnt lgkmcnt(0)
	v_mfma_f32_32x32x16_bf16 v[34:49], v[176:179], v[50:53], 0
	ds_read2_b64 v[216:219], v210 offset0:8 offset1:10
	ds_read2_b64 v[220:223], v211 offset0:8 offset1:10
	ds_read2_b64 v[224:227], v210 offset0:12 offset1:14
	ds_read2_b64 v[228:231], v211 offset0:12 offset1:14
	v_max3_f32 v152, v232, s22, v233
	v_max3_f32 v152, v152, v234, v235
	v_max3_f32 v152, v152, v236, v237
	v_max3_f32 v152, v152, v238, v239
	v_max3_f32 v152, v152, v240, v241
	v_max3_f32 v152, v152, v242, v243
	v_max3_f32 v152, v152, v244, v245
	v_max3_f32 v152, v152, v246, v247
	v_mfma_f32_32x32x16_bf16 v[34:49], v[180:183], v[54:57], v[34:49]
	v_mov_b32_e32 v153, v152
	s_nop 1
	v_permlane32_swap_b32_e32 v152, v153
	v_max_f32_e32 v152, v152, v153
	v_mul_f32_e32 v152, 0x3e38aa3b, v152
	v_max_f32_e32 v154, v71, v152
	v_sub_f32_e32 v0, v71, v154
	v_pk_fma_f32 v[232:233], v[232:233], s[22:23], v[154:155] op_sel:[0,1,0] op_sel_hi:[1,1,0] neg_lo:[0,0,1] neg_hi:[0,0,1]
	v_pk_fma_f32 v[234:235], v[234:235], s[22:23], v[154:155] op_sel:[0,1,0] op_sel_hi:[1,1,0] neg_lo:[0,0,1] neg_hi:[0,0,1]
	v_pk_fma_f32 v[236:237], v[236:237], s[22:23], v[154:155] op_sel:[0,1,0] op_sel_hi:[1,1,0] neg_lo:[0,0,1] neg_hi:[0,0,1]
	v_pk_fma_f32 v[238:239], v[238:239], s[22:23], v[154:155] op_sel:[0,1,0] op_sel_hi:[1,1,0] neg_lo:[0,0,1] neg_hi:[0,0,1]
	v_pk_fma_f32 v[240:241], v[240:241], s[22:23], v[154:155] op_sel:[0,1,0] op_sel_hi:[1,1,0] neg_lo:[0,0,1] neg_hi:[0,0,1]
	v_pk_fma_f32 v[242:243], v[242:243], s[22:23], v[154:155] op_sel:[0,1,0] op_sel_hi:[1,1,0] neg_lo:[0,0,1] neg_hi:[0,0,1]
	v_pk_fma_f32 v[244:245], v[244:245], s[22:23], v[154:155] op_sel:[0,1,0] op_sel_hi:[1,1,0] neg_lo:[0,0,1] neg_hi:[0,0,1]
	v_pk_fma_f32 v[246:247], v[246:247], s[22:23], v[154:155] op_sel:[0,1,0] op_sel_hi:[1,1,0] neg_lo:[0,0,1] neg_hi:[0,0,1]
	v_mfma_f32_32x32x16_bf16 v[34:49], v[184:187], v[58:61], v[34:49]
	v_exp_f32_e32 v0, v0
	v_exp_f32_e32 v232, v232
	v_exp_f32_e32 v233, v233
	v_exp_f32_e32 v234, v234
	v_exp_f32_e32 v235, v235
	v_exp_f32_e32 v236, v236
	v_exp_f32_e32 v237, v237
	v_exp_f32_e32 v238, v238
	v_mfma_f32_32x32x16_bf16 v[34:49], v[200:203], v[62:65], v[34:49]
	ds_read_b128 v[176:179], v248 offset:12288
	ds_read_b128 v[180:183], v249 offset:12288
	ds_read_b128 v[184:187], v250 offset:12288
	ds_read_b128 v[200:203], v251 offset:12288
	v_exp_f32_e32 v239, v239
	v_exp_f32_e32 v240, v240
	v_exp_f32_e32 v241, v241
	v_exp_f32_e32 v242, v242
	v_exp_f32_e32 v243, v243
	v_exp_f32_e32 v244, v244
	v_exp_f32_e32 v245, v245
	v_exp_f32_e32 v246, v246
	v_exp_f32_e32 v247, v247
	v_mov_b32_e32 v71, v154
	v_pk_add_f32 v[156:157], v[232:233], v[234:235]
	v_pk_add_f32 v[158:159], v[236:237], v[238:239]
	v_pk_add_f32 v[160:161], v[240:241], v[242:243]
	v_pk_add_f32 v[204:205], v[244:245], v[246:247]
	v_pk_add_f32 v[156:157], v[156:157], v[158:159]
	v_pk_add_f32 v[160:161], v[160:161], v[204:205]
	v_pk_add_f32 v[156:157], v[156:157], v[160:161]
	v_add_f32_e32 v206, v156, v157
	v_mov_b32_e32 v207, v206
	s_nop 1
	v_permlane32_swap_b32_e32 v206, v207
	v_cmp_neq_f32_e32 vcc, 1.0, v0
	s_cbranch_vccz .Lattn_qkeep_1
	v_pk_mul_f32 v[32:33], v[32:33], v[0:1] op_sel_hi:[1,0]
	v_pk_mul_f32 v[30:31], v[30:31], v[0:1] op_sel_hi:[1,0]
	v_pk_mul_f32 v[28:29], v[28:29], v[0:1] op_sel_hi:[1,0]
	v_pk_mul_f32 v[26:27], v[26:27], v[0:1] op_sel_hi:[1,0]
	v_pk_mul_f32 v[24:25], v[24:25], v[0:1] op_sel_hi:[1,0]
	v_pk_mul_f32 v[22:23], v[22:23], v[0:1] op_sel_hi:[1,0]
	v_pk_mul_f32 v[20:21], v[20:21], v[0:1] op_sel_hi:[1,0]
	v_pk_mul_f32 v[18:19], v[18:19], v[0:1] op_sel_hi:[1,0]
	v_pk_mul_f32 v[16:17], v[16:17], v[0:1] op_sel_hi:[1,0]
	v_pk_mul_f32 v[14:15], v[14:15], v[0:1] op_sel_hi:[1,0]
	v_pk_mul_f32 v[12:13], v[12:13], v[0:1] op_sel_hi:[1,0]
	v_pk_mul_f32 v[10:11], v[10:11], v[0:1] op_sel_hi:[1,0]
	v_pk_mul_f32 v[8:9], v[8:9], v[0:1] op_sel_hi:[1,0]
	v_pk_mul_f32 v[6:7], v[6:7], v[0:1] op_sel_hi:[1,0]
	v_pk_mul_f32 v[4:5], v[4:5], v[0:1] op_sel_hi:[1,0]
	v_pk_mul_f32 v[2:3], v[2:3], v[0:1] op_sel_hi:[1,0]
; DI unsigned pack2bf(float a, float b) { const f2_t v = {a, b}; return __builtin_bit_cast(unsigned, __builtin_convertvector(v, bf2_t)); }
; DI float xor32_max(float v) { const auto r = __builtin_amdgcn_permlane32_swap(__float_as_uint(v), __float_as_uint(v), false, false); return fmaxf(__uint_as_float(r[0]), __uint_as_float(r[1])); }
; DI int crow(int i, int hh) { return (i & 3) + 8 * (i >> 2) + 4 * hh; }
; DI void attn_task(const Params& P, int bh, int n, int t, int lane, const char* Ks, const char* Vs) {
;     ...
;     for (int s = 0; s < 4; ++s) {
;       const bf16x8 kf = *reinterpret_cast<const bf16x8*>(Ks + krow * 128 + (((2 * s + hh) ^ ((krow >> 1) & 7)) * 16));
;       S = __builtin_amdgcn_mfma_f32_32x32x16_bf16(kf, qf[s], S, 0, 0, 0);
;     }
;     const bool diag = own && (kt == t);
;     constexpr float SC2 = 0.125f * 1.4426950408889634f;
;     float mx = -1e30f;
; #pragma unroll
;     for (int i = 0; i < 16; ++i) {
;       if (diag && (kbase + crow(i, hh) > lq)) S[i] = -1e30f;
;       mx = fmaxf(mx, S[i]);
;     }
;     mx = xor32_max(mx);
;     const float m_new = fmaxf(m_run, mx * SC2);
;     const float alpha = __builtin_amdgcn_exp2f(m_run - m_new);
;     float rs = 0.f;
; #pragma unroll
;     for (int i = 0; i < 16; ++i) { float pv = __builtin_amdgcn_exp2f(fmaf(S[i], SC2, -m_new)); S[i] = pv; rs += pv; }
;     rs = xor32_sum(rs);
;     l_run = l_run * alpha + rs; m_run = m_new;
;     if (__ballot(alpha != 1.f)) {
; #pragma unroll
;       for (int i = 0; i < 16; ++i) { O0[i] *= alpha; O1[i] *= alpha; }
;     }
; #pragma unroll
;     for (int s = 0; s < 2; ++s) {
;       const uint4 ppk = make_uint4(pack2bf(S[8 * s], S[8 * s + 1]), pack2bf(S[8 * s + 2], S[8 * s + 3]), pack2bf(S[8 * s + 4], S[8 * s + 5]), pack2bf(S[8 * s + 6], S[8 * s + 7]));
;       const bf16x8 pf = __builtin_bit_cast(bf16x8, ppk);
; #pragma unroll
;       for (int dt = 0; dt < 2; ++dt) {
;         const char* vp = Vs + (dt * 32 + r) * 528 + (kt * 32 + 16 * s + 4 * hh) * 2;
;         const uint2 lo = *reinterpret_cast<const uint2*>(vp), hi = *reinterpret_cast<const uint2*>(vp + 16);
;         const uint4 vv = make_uint4(lo.x, lo.y, hi.x, hi.y);
;         if (dt == 0) O0 = __builtin_amdgcn_mfma_f32_32x32x16_bf16(__builtin_bit_cast(bf16x8, vv), pf, O0, 0, 0, 0);
;         else O1 = __builtin_amdgcn_mfma_f32_32x32x16_bf16(__builtin_bit_cast(bf16x8, vv), pf, O1, 0, 0, 0);
;       }
.Lattn_qkeep_1:
	v_add_f32_e32 v252, v206, v207
	v_fmac_f32_e32 v252, v151, v0
	v_cvt_pk_bf16_f32 v156, v232, v233
	v_cvt_pk_bf16_f32 v157, v234, v235
	v_cvt_pk_bf16_f32 v158, v236, v237
	v_cvt_pk_bf16_f32 v159, v238, v239
	v_cvt_pk_bf16_f32 v152, v240, v241
	v_cvt_pk_bf16_f32 v153, v242, v243
	v_cvt_pk_bf16_f32 v154, v244, v245
	v_cvt_pk_bf16_f32 v155, v246, v247
	v_mov_b32_e32 v151, v252
	s_waitcnt lgkmcnt(0)
	v_mfma_f32_32x32x16_bf16 v[18:33], v[216:219], v[156:159], v[18:33]
	v_mfma_f32_32x32x16_bf16 v[2:17], v[220:223], v[156:159], v[2:17]
	v_mfma_f32_32x32x16_bf16 v[18:33], v[224:227], v[152:155], v[18:33]
	v_mfma_f32_32x32x16_bf16 v[2:17], v[228:231], v[152:155], v[2:17]
	s_waitcnt lgkmcnt(0)
	v_mfma_f32_32x32x16_bf16 v[232:247], v[176:179], v[50:53], 0
	ds_read2_b64 v[216:219], v210 offset0:16 offset1:18
	ds_read2_b64 v[220:223], v211 offset0:16 offset1:18
	ds_read2_b64 v[224:227], v210 offset0:20 offset1:22
	ds_read2_b64 v[228:231], v211 offset0:20 offset1:22
	v_max3_f32 v152, v34, s22, v35
	v_max3_f32 v152, v152, v36, v37
	v_max3_f32 v152, v152, v38, v39
	v_max3_f32 v152, v152, v40, v41
	v_max3_f32 v152, v152, v42, v43
	v_max3_f32 v152, v152, v44, v45
	v_max3_f32 v152, v152, v46, v47
	v_max3_f32 v152, v152, v48, v49
	v_mfma_f32_32x32x16_bf16 v[232:247], v[180:183], v[54:57], v[232:247]
	v_mov_b32_e32 v153, v152
	s_nop 1
	v_permlane32_swap_b32_e32 v152, v153
	v_max_f32_e32 v152, v152, v153
	v_mul_f32_e32 v152, 0x3e38aa3b, v152
	v_max_f32_e32 v154, v71, v152
	v_sub_f32_e32 v0, v71, v154
	v_pk_fma_f32 v[34:35], v[34:35], s[22:23], v[154:155] op_sel:[0,1,0] op_sel_hi:[1,1,0] neg_lo:[0,0,1] neg_hi:[0,0,1]
	v_pk_fma_f32 v[36:37], v[36:37], s[22:23], v[154:155] op_sel:[0,1,0] op_sel_hi:[1,1,0] neg_lo:[0,0,1] neg_hi:[0,0,1]
	v_pk_fma_f32 v[38:39], v[38:39], s[22:23], v[154:155] op_sel:[0,1,0] op_sel_hi:[1,1,0] neg_lo:[0,0,1] neg_hi:[0,0,1]
	v_pk_fma_f32 v[40:41], v[40:41], s[22:23], v[154:155] op_sel:[0,1,0] op_sel_hi:[1,1,0] neg_lo:[0,0,1] neg_hi:[0,0,1]
	v_pk_fma_f32 v[42:43], v[42:43], s[22:23], v[154:155] op_sel:[0,1,0] op_sel_hi:[1,1,0] neg_lo:[0,0,1] neg_hi:[0,0,1]
	v_pk_fma_f32 v[44:45], v[44:45], s[22:23], v[154:155] op_sel:[0,1,0] op_sel_hi:[1,1,0] neg_lo:[0,0,1] neg_hi:[0,0,1]
	v_pk_fma_f32 v[46:47], v[46:47], s[22:23], v[154:155] op_sel:[0,1,0] op_sel_hi:[1,1,0] neg_lo:[0,0,1] neg_hi:[0,0,1]
	v_pk_fma_f32 v[48:49], v[48:49], s[22:23], v[154:155] op_sel:[0,1,0] op_sel_hi:[1,1,0] neg_lo:[0,0,1] neg_hi:[0,0,1]
	v_mfma_f32_32x32x16_bf16 v[232:247], v[184:187], v[58:61], v[232:247]
	v_exp_f32_e32 v0, v0
	v_exp_f32_e32 v34, v34
	v_exp_f32_e32 v35, v35
	v_exp_f32_e32 v36, v36
	v_exp_f32_e32 v37, v37
	v_exp_f32_e32 v38, v38
	v_exp_f32_e32 v39, v39
	v_exp_f32_e32 v40, v40
	v_mfma_f32_32x32x16_bf16 v[232:247], v[200:203], v[62:65], v[232:247]
	ds_read_b128 v[176:179], v248 offset:16384
	ds_read_b128 v[180:183], v249 offset:16384
	ds_read_b128 v[184:187], v250 offset:16384
	ds_read_b128 v[200:203], v251 offset:16384
	v_exp_f32_e32 v41, v41
	v_exp_f32_e32 v42, v42
	v_exp_f32_e32 v43, v43
	v_exp_f32_e32 v44, v44
	v_exp_f32_e32 v45, v45
	v_exp_f32_e32 v46, v46
	v_exp_f32_e32 v47, v47
	v_exp_f32_e32 v48, v48
	v_exp_f32_e32 v49, v49
	v_mov_b32_e32 v71, v154
	v_pk_add_f32 v[156:157], v[34:35], v[36:37]
	v_pk_add_f32 v[158:159], v[38:39], v[40:41]
	v_pk_add_f32 v[160:161], v[42:43], v[44:45]
	v_pk_add_f32 v[204:205], v[46:47], v[48:49]
	v_pk_add_f32 v[156:157], v[156:157], v[158:159]
	v_pk_add_f32 v[160:161], v[160:161], v[204:205]
	v_pk_add_f32 v[156:157], v[156:157], v[160:161]
	v_add_f32_e32 v206, v156, v157
	v_mov_b32_e32 v207, v206
	s_nop 1
	v_permlane32_swap_b32_e32 v206, v207
	v_cmp_neq_f32_e32 vcc, 1.0, v0
	s_cbranch_vccz .Lattn_qkeep_2
	v_pk_mul_f32 v[32:33], v[32:33], v[0:1] op_sel_hi:[1,0]
	v_pk_mul_f32 v[30:31], v[30:31], v[0:1] op_sel_hi:[1,0]
	v_pk_mul_f32 v[28:29], v[28:29], v[0:1] op_sel_hi:[1,0]
	v_pk_mul_f32 v[26:27], v[26:27], v[0:1] op_sel_hi:[1,0]
	v_pk_mul_f32 v[24:25], v[24:25], v[0:1] op_sel_hi:[1,0]
	v_pk_mul_f32 v[22:23], v[22:23], v[0:1] op_sel_hi:[1,0]
	v_pk_mul_f32 v[20:21], v[20:21], v[0:1] op_sel_hi:[1,0]
	v_pk_mul_f32 v[18:19], v[18:19], v[0:1] op_sel_hi:[1,0]
	v_pk_mul_f32 v[16:17], v[16:17], v[0:1] op_sel_hi:[1,0]
	v_pk_mul_f32 v[14:15], v[14:15], v[0:1] op_sel_hi:[1,0]
	v_pk_mul_f32 v[12:13], v[12:13], v[0:1] op_sel_hi:[1,0]
	v_pk_mul_f32 v[10:11], v[10:11], v[0:1] op_sel_hi:[1,0]
	v_pk_mul_f32 v[8:9], v[8:9], v[0:1] op_sel_hi:[1,0]
	v_pk_mul_f32 v[6:7], v[6:7], v[0:1] op_sel_hi:[1,0]
	v_pk_mul_f32 v[4:5], v[4:5], v[0:1] op_sel_hi:[1,0]
	v_pk_mul_f32 v[2:3], v[2:3], v[0:1] op_sel_hi:[1,0]
; DI unsigned pack2bf(float a, float b) { const f2_t v = {a, b}; return __builtin_bit_cast(unsigned, __builtin_convertvector(v, bf2_t)); }
; DI float xor32_max(float v) { const auto r = __builtin_amdgcn_permlane32_swap(__float_as_uint(v), __float_as_uint(v), false, false); return fmaxf(__uint_as_float(r[0]), __uint_as_float(r[1])); }
; DI int crow(int i, int hh) { return (i & 3) + 8 * (i >> 2) + 4 * hh; }
; DI void attn_task(const Params& P, int bh, int n, int t, int lane, const char* Ks, const char* Vs) {
;     ...
;     for (int s = 0; s < 4; ++s) {
;       const bf16x8 kf = *reinterpret_cast<const bf16x8*>(Ks + krow * 128 + (((2 * s + hh) ^ ((krow >> 1) & 7)) * 16));
;       S = __builtin_amdgcn_mfma_f32_32x32x16_bf16(kf, qf[s], S, 0, 0, 0);
;     }
;     const bool diag = own && (kt == t);
;     constexpr float SC2 = 0.125f * 1.4426950408889634f;
;     float mx = -1e30f;
; #pragma unroll
;     for (int i = 0; i < 16; ++i) {
;       if (diag && (kbase + crow(i, hh) > lq)) S[i] = -1e30f;
;       mx = fmaxf(mx, S[i]);
;     }
;     mx = xor32_max(mx);
;     const float m_new = fmaxf(m_run, mx * SC2);
;     const float alpha = __builtin_amdgcn_exp2f(m_run - m_new);
;     float rs = 0.f;
; #pragma unroll
;     for (int i = 0; i < 16; ++i) { float pv = __builtin_amdgcn_exp2f(fmaf(S[i], SC2, -m_new)); S[i] = pv; rs += pv; }
;     rs = xor32_sum(rs);
;     l_run = l_run * alpha + rs; m_run = m_new;
;     if (__ballot(alpha != 1.f)) {
; #pragma unroll
;       for (int i = 0; i < 16; ++i) { O0[i] *= alpha; O1[i] *= alpha; }
;     }
; #pragma unroll
;     for (int s = 0; s < 2; ++s) {
;       const uint4 ppk = make_uint4(pack2bf(S[8 * s], S[8 * s + 1]), pack2bf(S[8 * s + 2], S[8 * s + 3]), pack2bf(S[8 * s + 4], S[8 * s + 5]), pack2bf(S[8 * s + 6], S[8 * s + 7]));
;       const bf16x8 pf = __builtin_bit_cast(bf16x8, ppk);
; #pragma unroll
;       for (int dt = 0; dt < 2; ++dt) {
;         const char* vp = Vs + (dt * 32 + r) * 528 + (kt * 32 + 16 * s + 4 * hh) * 2;
;         const uint2 lo = *reinterpret_cast<const uint2*>(vp), hi = *reinterpret_cast<const uint2*>(vp + 16);
;         const uint4 vv = make_uint4(lo.x, lo.y, hi.x, hi.y);
;         if (dt == 0) O0 = __builtin_amdgcn_mfma_f32_32x32x16_bf16(__builtin_bit_cast(bf16x8, vv), pf, O0, 0, 0, 0);
;         else O1 = __builtin_amdgcn_mfma_f32_32x32x16_bf16(__builtin_bit_cast(bf16x8, vv), pf, O1, 0, 0, 0);
;       }
.Lattn_qkeep_2:
	v_add_f32_e32 v252, v206, v207
	v_fmac_f32_e32 v252, v151, v0
	v_cvt_pk_bf16_f32 v156, v34, v35
	v_cvt_pk_bf16_f32 v157, v36, v37
	v_cvt_pk_bf16_f32 v158, v38, v39
	v_cvt_pk_bf16_f32 v159, v40, v41
	v_cvt_pk_bf16_f32 v152, v42, v43
	v_cvt_pk_bf16_f32 v153, v44, v45
	v_cvt_pk_bf16_f32 v154, v46, v47
	v_cvt_pk_bf16_f32 v155, v48, v49
	v_mov_b32_e32 v151, v252
	s_waitcnt lgkmcnt(0)
	v_mfma_f32_32x32x16_bf16 v[18:33], v[216:219], v[156:159], v[18:33]
	v_mfma_f32_32x32x16_bf16 v[2:17], v[220:223], v[156:159], v[2:17]
	v_mfma_f32_32x32x16_bf16 v[18:33], v[224:227], v[152:155], v[18:33]
	v_mfma_f32_32x32x16_bf16 v[2:17], v[228:231], v[152:155], v[2:17]
	s_waitcnt lgkmcnt(0)
	v_mfma_f32_32x32x16_bf16 v[34:49], v[176:179], v[50:53], 0
	ds_read2_b64 v[216:219], v210 offset0:24 offset1:26
	ds_read2_b64 v[220:223], v211 offset0:24 offset1:26
	ds_read2_b64 v[224:227], v210 offset0:28 offset1:30
	ds_read2_b64 v[228:231], v211 offset0:28 offset1:30
	v_max3_f32 v152, v232, s22, v233
	v_max3_f32 v152, v152, v234, v235
	v_max3_f32 v152, v152, v236, v237
	v_max3_f32 v152, v152, v238, v239
	v_max3_f32 v152, v152, v240, v241
	v_max3_f32 v152, v152, v242, v243
	v_max3_f32 v152, v152, v244, v245
	v_max3_f32 v152, v152, v246, v247
	v_mfma_f32_32x32x16_bf16 v[34:49], v[180:183], v[54:57], v[34:49]
	v_mov_b32_e32 v153, v152
	s_nop 1
	v_permlane32_swap_b32_e32 v152, v153
	v_max_f32_e32 v152, v152, v153
	v_mul_f32_e32 v152, 0x3e38aa3b, v152
	v_max_f32_e32 v154, v71, v152
	v_sub_f32_e32 v0, v71, v154
	v_pk_fma_f32 v[232:233], v[232:233], s[22:23], v[154:155] op_sel:[0,1,0] op_sel_hi:[1,1,0] neg_lo:[0,0,1] neg_hi:[0,0,1]
	v_pk_fma_f32 v[234:235], v[234:235], s[22:23], v[154:155] op_sel:[0,1,0] op_sel_hi:[1,1,0] neg_lo:[0,0,1] neg_hi:[0,0,1]
	v_pk_fma_f32 v[236:237], v[236:237], s[22:23], v[154:155] op_sel:[0,1,0] op_sel_hi:[1,1,0] neg_lo:[0,0,1] neg_hi:[0,0,1]
	v_pk_fma_f32 v[238:239], v[238:239], s[22:23], v[154:155] op_sel:[0,1,0] op_sel_hi:[1,1,0] neg_lo:[0,0,1] neg_hi:[0,0,1]
	v_pk_fma_f32 v[240:241], v[240:241], s[22:23], v[154:155] op_sel:[0,1,0] op_sel_hi:[1,1,0] neg_lo:[0,0,1] neg_hi:[0,0,1]
	v_pk_fma_f32 v[242:243], v[242:243], s[22:23], v[154:155] op_sel:[0,1,0] op_sel_hi:[1,1,0] neg_lo:[0,0,1] neg_hi:[0,0,1]
	v_pk_fma_f32 v[244:245], v[244:245], s[22:23], v[154:155] op_sel:[0,1,0] op_sel_hi:[1,1,0] neg_lo:[0,0,1] neg_hi:[0,0,1]
	v_pk_fma_f32 v[246:247], v[246:247], s[22:23], v[154:155] op_sel:[0,1,0] op_sel_hi:[1,1,0] neg_lo:[0,0,1] neg_hi:[0,0,1]
	v_mfma_f32_32x32x16_bf16 v[34:49], v[184:187], v[58:61], v[34:49]
	v_exp_f32_e32 v0, v0
	v_exp_f32_e32 v232, v232
	v_exp_f32_e32 v233, v233
	v_exp_f32_e32 v234, v234
	v_exp_f32_e32 v235, v235
	v_exp_f32_e32 v236, v236
	v_exp_f32_e32 v237, v237
	v_exp_f32_e32 v238, v238
	v_mfma_f32_32x32x16_bf16 v[34:49], v[200:203], v[62:65], v[34:49]
	ds_read_b128 v[176:179], v248 offset:20480
	ds_read_b128 v[180:183], v249 offset:20480
	ds_read_b128 v[184:187], v250 offset:20480
	ds_read_b128 v[200:203], v251 offset:20480
	v_exp_f32_e32 v239, v239
	v_exp_f32_e32 v240, v240
	v_exp_f32_e32 v241, v241
	v_exp_f32_e32 v242, v242
	v_exp_f32_e32 v243, v243
	v_exp_f32_e32 v244, v244
	v_exp_f32_e32 v245, v245
	v_exp_f32_e32 v246, v246
	v_exp_f32_e32 v247, v247
	v_mov_b32_e32 v71, v154
	v_pk_add_f32 v[156:157], v[232:233], v[234:235]
	v_pk_add_f32 v[158:159], v[236:237], v[238:239]
	v_pk_add_f32 v[160:161], v[240:241], v[242:243]
	v_pk_add_f32 v[204:205], v[244:245], v[246:247]
	v_pk_add_f32 v[156:157], v[156:157], v[158:159]
	v_pk_add_f32 v[160:161], v[160:161], v[204:205]
	v_pk_add_f32 v[156:157], v[156:157], v[160:161]
	v_add_f32_e32 v206, v156, v157
	v_mov_b32_e32 v207, v206
	s_nop 1
	v_permlane32_swap_b32_e32 v206, v207
	v_cmp_neq_f32_e32 vcc, 1.0, v0
	s_cbranch_vccz .Lattn_qkeep_3
	v_pk_mul_f32 v[32:33], v[32:33], v[0:1] op_sel_hi:[1,0]
	v_pk_mul_f32 v[30:31], v[30:31], v[0:1] op_sel_hi:[1,0]
	v_pk_mul_f32 v[28:29], v[28:29], v[0:1] op_sel_hi:[1,0]
	v_pk_mul_f32 v[26:27], v[26:27], v[0:1] op_sel_hi:[1,0]
	v_pk_mul_f32 v[24:25], v[24:25], v[0:1] op_sel_hi:[1,0]
	v_pk_mul_f32 v[22:23], v[22:23], v[0:1] op_sel_hi:[1,0]
	v_pk_mul_f32 v[20:21], v[20:21], v[0:1] op_sel_hi:[1,0]
	v_pk_mul_f32 v[18:19], v[18:19], v[0:1] op_sel_hi:[1,0]
	v_pk_mul_f32 v[16:17], v[16:17], v[0:1] op_sel_hi:[1,0]
	v_pk_mul_f32 v[14:15], v[14:15], v[0:1] op_sel_hi:[1,0]
	v_pk_mul_f32 v[12:13], v[12:13], v[0:1] op_sel_hi:[1,0]
	v_pk_mul_f32 v[10:11], v[10:11], v[0:1] op_sel_hi:[1,0]
	v_pk_mul_f32 v[8:9], v[8:9], v[0:1] op_sel_hi:[1,0]
	v_pk_mul_f32 v[6:7], v[6:7], v[0:1] op_sel_hi:[1,0]
	v_pk_mul_f32 v[4:5], v[4:5], v[0:1] op_sel_hi:[1,0]
	v_pk_mul_f32 v[2:3], v[2:3], v[0:1] op_sel_hi:[1,0]
; DI unsigned pack2bf(float a, float b) { const f2_t v = {a, b}; return __builtin_bit_cast(unsigned, __builtin_convertvector(v, bf2_t)); }
; DI float xor32_max(float v) { const auto r = __builtin_amdgcn_permlane32_swap(__float_as_uint(v), __float_as_uint(v), false, false); return fmaxf(__uint_as_float(r[0]), __uint_as_float(r[1])); }
; DI int crow(int i, int hh) { return (i & 3) + 8 * (i >> 2) + 4 * hh; }
; DI void attn_task(const Params& P, int bh, int n, int t, int lane, const char* Ks, const char* Vs) {
;     ...
;     for (int s = 0; s < 4; ++s) {
;       const bf16x8 kf = *reinterpret_cast<const bf16x8*>(Ks + krow * 128 + (((2 * s + hh) ^ ((krow >> 1) & 7)) * 16));
;       S = __builtin_amdgcn_mfma_f32_32x32x16_bf16(kf, qf[s], S, 0, 0, 0);
;     }
;     const bool diag = own && (kt == t);
;     constexpr float SC2 = 0.125f * 1.4426950408889634f;
;     float mx = -1e30f;
; #pragma unroll
;     for (int i = 0; i < 16; ++i) {
;       if (diag && (kbase + crow(i, hh) > lq)) S[i] = -1e30f;
;       mx = fmaxf(mx, S[i]);
;     }
;     mx = xor32_max(mx);
;     const float m_new = fmaxf(m_run, mx * SC2);
;     const float alpha = __builtin_amdgcn_exp2f(m_run - m_new);
;     float rs = 0.f;
; #pragma unroll
;     for (int i = 0; i < 16; ++i) { float pv = __builtin_amdgcn_exp2f(fmaf(S[i], SC2, -m_new)); S[i] = pv; rs += pv; }
;     rs = xor32_sum(rs);
;     l_run = l_run * alpha + rs; m_run = m_new;
;     if (__ballot(alpha != 1.f)) {
; #pragma unroll
;       for (int i = 0; i < 16; ++i) { O0[i] *= alpha; O1[i] *= alpha; }
;     }
; #pragma unroll
;     for (int s = 0; s < 2; ++s) {
;       const uint4 ppk = make_uint4(pack2bf(S[8 * s], S[8 * s + 1]), pack2bf(S[8 * s + 2], S[8 * s + 3]), pack2bf(S[8 * s + 4], S[8 * s + 5]), pack2bf(S[8 * s + 6], S[8 * s + 7]));
;       const bf16x8 pf = __builtin_bit_cast(bf16x8, ppk);
; #pragma unroll
;       for (int dt = 0; dt < 2; ++dt) {
;         const char* vp = Vs + (dt * 32 + r) * 528 + (kt * 32 + 16 * s + 4 * hh) * 2;
;         const uint2 lo = *reinterpret_cast<const uint2*>(vp), hi = *reinterpret_cast<const uint2*>(vp + 16);
;         const uint4 vv = make_uint4(lo.x, lo.y, hi.x, hi.y);
;         if (dt == 0) O0 = __builtin_amdgcn_mfma_f32_32x32x16_bf16(__builtin_bit_cast(bf16x8, vv), pf, O0, 0, 0, 0);
;         else O1 = __builtin_amdgcn_mfma_f32_32x32x16_bf16(__builtin_bit_cast(bf16x8, vv), pf, O1, 0, 0, 0);
;       }
.Lattn_qkeep_3:
	v_add_f32_e32 v252, v206, v207
	v_fmac_f32_e32 v252, v151, v0
	v_cvt_pk_bf16_f32 v156, v232, v233
	v_cvt_pk_bf16_f32 v157, v234, v235
	v_cvt_pk_bf16_f32 v158, v236, v237
	v_cvt_pk_bf16_f32 v159, v238, v239
	v_cvt_pk_bf16_f32 v152, v240, v241
	v_cvt_pk_bf16_f32 v153, v242, v243
	v_cvt_pk_bf16_f32 v154, v244, v245
	v_cvt_pk_bf16_f32 v155, v246, v247
	v_mov_b32_e32 v151, v252
	s_waitcnt lgkmcnt(0)
	v_mfma_f32_32x32x16_bf16 v[18:33], v[216:219], v[156:159], v[18:33]
	v_mfma_f32_32x32x16_bf16 v[2:17], v[220:223], v[156:159], v[2:17]
	v_mfma_f32_32x32x16_bf16 v[18:33], v[224:227], v[152:155], v[18:33]
	v_mfma_f32_32x32x16_bf16 v[2:17], v[228:231], v[152:155], v[2:17]
	s_waitcnt lgkmcnt(0)
	v_mfma_f32_32x32x16_bf16 v[232:247], v[176:179], v[50:53], 0
	ds_read2_b64 v[216:219], v210 offset0:32 offset1:34
	ds_read2_b64 v[220:223], v211 offset0:32 offset1:34
	ds_read2_b64 v[224:227], v210 offset0:36 offset1:38
	ds_read2_b64 v[228:231], v211 offset0:36 offset1:38
	v_max3_f32 v152, v34, s22, v35
	v_max3_f32 v152, v152, v36, v37
	v_max3_f32 v152, v152, v38, v39
	v_max3_f32 v152, v152, v40, v41
	v_max3_f32 v152, v152, v42, v43
	v_max3_f32 v152, v152, v44, v45
	v_max3_f32 v152, v152, v46, v47
	v_max3_f32 v152, v152, v48, v49
	v_mfma_f32_32x32x16_bf16 v[232:247], v[180:183], v[54:57], v[232:247]
	v_mov_b32_e32 v153, v152
	s_nop 1
	v_permlane32_swap_b32_e32 v152, v153
	v_max_f32_e32 v152, v152, v153
	v_mul_f32_e32 v152, 0x3e38aa3b, v152
	v_max_f32_e32 v154, v71, v152
	v_sub_f32_e32 v0, v71, v154
	v_pk_fma_f32 v[34:35], v[34:35], s[22:23], v[154:155] op_sel:[0,1,0] op_sel_hi:[1,1,0] neg_lo:[0,0,1] neg_hi:[0,0,1]
	v_pk_fma_f32 v[36:37], v[36:37], s[22:23], v[154:155] op_sel:[0,1,0] op_sel_hi:[1,1,0] neg_lo:[0,0,1] neg_hi:[0,0,1]
	v_pk_fma_f32 v[38:39], v[38:39], s[22:23], v[154:155] op_sel:[0,1,0] op_sel_hi:[1,1,0] neg_lo:[0,0,1] neg_hi:[0,0,1]
	v_pk_fma_f32 v[40:41], v[40:41], s[22:23], v[154:155] op_sel:[0,1,0] op_sel_hi:[1,1,0] neg_lo:[0,0,1] neg_hi:[0,0,1]
	v_pk_fma_f32 v[42:43], v[42:43], s[22:23], v[154:155] op_sel:[0,1,0] op_sel_hi:[1,1,0] neg_lo:[0,0,1] neg_hi:[0,0,1]
	v_pk_fma_f32 v[44:45], v[44:45], s[22:23], v[154:155] op_sel:[0,1,0] op_sel_hi:[1,1,0] neg_lo:[0,0,1] neg_hi:[0,0,1]
	v_pk_fma_f32 v[46:47], v[46:47], s[22:23], v[154:155] op_sel:[0,1,0] op_sel_hi:[1,1,0] neg_lo:[0,0,1] neg_hi:[0,0,1]
	v_pk_fma_f32 v[48:49], v[48:49], s[22:23], v[154:155] op_sel:[0,1,0] op_sel_hi:[1,1,0] neg_lo:[0,0,1] neg_hi:[0,0,1]
	v_mfma_f32_32x32x16_bf16 v[232:247], v[184:187], v[58:61], v[232:247]
	v_exp_f32_e32 v0, v0
	v_exp_f32_e32 v34, v34
	v_exp_f32_e32 v35, v35
	v_exp_f32_e32 v36, v36
	v_exp_f32_e32 v37, v37
	v_exp_f32_e32 v38, v38
	v_exp_f32_e32 v39, v39
	v_exp_f32_e32 v40, v40
	v_mfma_f32_32x32x16_bf16 v[232:247], v[200:203], v[62:65], v[232:247]
	ds_read_b128 v[176:179], v248 offset:24576
	ds_read_b128 v[180:183], v249 offset:24576
	ds_read_b128 v[184:187], v250 offset:24576
	ds_read_b128 v[200:203], v251 offset:24576
	v_exp_f32_e32 v41, v41
	v_exp_f32_e32 v42, v42
	v_exp_f32_e32 v43, v43
	v_exp_f32_e32 v44, v44
	v_exp_f32_e32 v45, v45
	v_exp_f32_e32 v46, v46
	v_exp_f32_e32 v47, v47
	v_exp_f32_e32 v48, v48
	v_exp_f32_e32 v49, v49
	v_mov_b32_e32 v71, v154
	v_pk_add_f32 v[156:157], v[34:35], v[36:37]
	v_pk_add_f32 v[158:159], v[38:39], v[40:41]
	v_pk_add_f32 v[160:161], v[42:43], v[44:45]
	v_pk_add_f32 v[204:205], v[46:47], v[48:49]
	v_pk_add_f32 v[156:157], v[156:157], v[158:159]
	v_pk_add_f32 v[160:161], v[160:161], v[204:205]
	v_pk_add_f32 v[156:157], v[156:157], v[160:161]
	v_add_f32_e32 v206, v156, v157
	v_mov_b32_e32 v207, v206
	s_nop 1
	v_permlane32_swap_b32_e32 v206, v207
	v_cmp_neq_f32_e32 vcc, 1.0, v0
	s_cbranch_vccz .Lattn_qkeep_4
	v_pk_mul_f32 v[32:33], v[32:33], v[0:1] op_sel_hi:[1,0]
	v_pk_mul_f32 v[30:31], v[30:31], v[0:1] op_sel_hi:[1,0]
	v_pk_mul_f32 v[28:29], v[28:29], v[0:1] op_sel_hi:[1,0]
	v_pk_mul_f32 v[26:27], v[26:27], v[0:1] op_sel_hi:[1,0]
	v_pk_mul_f32 v[24:25], v[24:25], v[0:1] op_sel_hi:[1,0]
	v_pk_mul_f32 v[22:23], v[22:23], v[0:1] op_sel_hi:[1,0]
	v_pk_mul_f32 v[20:21], v[20:21], v[0:1] op_sel_hi:[1,0]
	v_pk_mul_f32 v[18:19], v[18:19], v[0:1] op_sel_hi:[1,0]
	v_pk_mul_f32 v[16:17], v[16:17], v[0:1] op_sel_hi:[1,0]
	v_pk_mul_f32 v[14:15], v[14:15], v[0:1] op_sel_hi:[1,0]
	v_pk_mul_f32 v[12:13], v[12:13], v[0:1] op_sel_hi:[1,0]
	v_pk_mul_f32 v[10:11], v[10:11], v[0:1] op_sel_hi:[1,0]
	v_pk_mul_f32 v[8:9], v[8:9], v[0:1] op_sel_hi:[1,0]
	v_pk_mul_f32 v[6:7], v[6:7], v[0:1] op_sel_hi:[1,0]
	v_pk_mul_f32 v[4:5], v[4:5], v[0:1] op_sel_hi:[1,0]
	v_pk_mul_f32 v[2:3], v[2:3], v[0:1] op_sel_hi:[1,0]
; DI unsigned pack2bf(float a, float b) { const f2_t v = {a, b}; return __builtin_bit_cast(unsigned, __builtin_convertvector(v, bf2_t)); }
; DI float xor32_max(float v) { const auto r = __builtin_amdgcn_permlane32_swap(__float_as_uint(v), __float_as_uint(v), false, false); return fmaxf(__uint_as_float(r[0]), __uint_as_float(r[1])); }
; DI int crow(int i, int hh) { return (i & 3) + 8 * (i >> 2) + 4 * hh; }
; DI void attn_task(const Params& P, int bh, int n, int t, int lane, const char* Ks, const char* Vs) {
;     ...
;     for (int s = 0; s < 4; ++s) {
;       const bf16x8 kf = *reinterpret_cast<const bf16x8*>(Ks + krow * 128 + (((2 * s + hh) ^ ((krow >> 1) & 7)) * 16));
;       S = __builtin_amdgcn_mfma_f32_32x32x16_bf16(kf, qf[s], S, 0, 0, 0);
;     }
;     const bool diag = own && (kt == t);
;     constexpr float SC2 = 0.125f * 1.4426950408889634f;
;     float mx = -1e30f;
; #pragma unroll
;     for (int i = 0; i < 16; ++i) {
;       if (diag && (kbase + crow(i, hh) > lq)) S[i] = -1e30f;
;       mx = fmaxf(mx, S[i]);
;     }
;     mx = xor32_max(mx);
;     const float m_new = fmaxf(m_run, mx * SC2);
;     const float alpha = __builtin_amdgcn_exp2f(m_run - m_new);
;     float rs = 0.f;
; #pragma unroll
;     for (int i = 0; i < 16; ++i) { float pv = __builtin_amdgcn_exp2f(fmaf(S[i], SC2, -m_new)); S[i] = pv; rs += pv; }
;     rs = xor32_sum(rs);
;     l_run = l_run * alpha + rs; m_run = m_new;
;     if (__ballot(alpha != 1.f)) {
; #pragma unroll
;       for (int i = 0; i < 16; ++i) { O0[i] *= alpha; O1[i] *= alpha; }
;     }
; #pragma unroll
;     for (int s = 0; s < 2; ++s) {
;       const uint4 ppk = make_uint4(pack2bf(S[8 * s], S[8 * s + 1]), pack2bf(S[8 * s + 2], S[8 * s + 3]), pack2bf(S[8 * s + 4], S[8 * s + 5]), pack2bf(S[8 * s + 6], S[8 * s + 7]));
;       const bf16x8 pf = __builtin_bit_cast(bf16x8, ppk);
; #pragma unroll
;       for (int dt = 0; dt < 2; ++dt) {
;         const char* vp = Vs + (dt * 32 + r) * 528 + (kt * 32 + 16 * s + 4 * hh) * 2;
;         const uint2 lo = *reinterpret_cast<const uint2*>(vp), hi = *reinterpret_cast<const uint2*>(vp + 16);
;         const uint4 vv = make_uint4(lo.x, lo.y, hi.x, hi.y);
;         if (dt == 0) O0 = __builtin_amdgcn_mfma_f32_32x32x16_bf16(__builtin_bit_cast(bf16x8, vv), pf, O0, 0, 0, 0);
;         else O1 = __builtin_amdgcn_mfma_f32_32x32x16_bf16(__builtin_bit_cast(bf16x8, vv), pf, O1, 0, 0, 0);
;       }
.Lattn_qkeep_4:
	v_add_f32_e32 v252, v206, v207
	v_fmac_f32_e32 v252, v151, v0
	v_cvt_pk_bf16_f32 v156, v34, v35
	v_cvt_pk_bf16_f32 v157, v36, v37
	v_cvt_pk_bf16_f32 v158, v38, v39
	v_cvt_pk_bf16_f32 v159, v40, v41
	v_cvt_pk_bf16_f32 v152, v42, v43
	v_cvt_pk_bf16_f32 v153, v44, v45
	v_cvt_pk_bf16_f32 v154, v46, v47
	v_cvt_pk_bf16_f32 v155, v48, v49
	v_mov_b32_e32 v151, v252
	s_waitcnt lgkmcnt(0)
	v_mfma_f32_32x32x16_bf16 v[18:33], v[216:219], v[156:159], v[18:33]
	v_mfma_f32_32x32x16_bf16 v[2:17], v[220:223], v[156:159], v[2:17]
	v_mfma_f32_32x32x16_bf16 v[18:33], v[224:227], v[152:155], v[18:33]
	v_mfma_f32_32x32x16_bf16 v[2:17], v[228:231], v[152:155], v[2:17]
	s_waitcnt lgkmcnt(0)
	v_mfma_f32_32x32x16_bf16 v[34:49], v[176:179], v[50:53], 0
	ds_read2_b64 v[216:219], v210 offset0:40 offset1:42
	ds_read2_b64 v[220:223], v211 offset0:40 offset1:42
	ds_read2_b64 v[224:227], v210 offset0:44 offset1:46
	ds_read2_b64 v[228:231], v211 offset0:44 offset1:46
	v_max3_f32 v152, v232, s22, v233
	v_max3_f32 v152, v152, v234, v235
	v_max3_f32 v152, v152, v236, v237
	v_max3_f32 v152, v152, v238, v239
	v_max3_f32 v152, v152, v240, v241
	v_max3_f32 v152, v152, v242, v243
	v_max3_f32 v152, v152, v244, v245
	v_max3_f32 v152, v152, v246, v247
	v_mfma_f32_32x32x16_bf16 v[34:49], v[180:183], v[54:57], v[34:49]
	v_mov_b32_e32 v153, v152
	s_nop 1
	v_permlane32_swap_b32_e32 v152, v153
	v_max_f32_e32 v152, v152, v153
	v_mul_f32_e32 v152, 0x3e38aa3b, v152
	v_max_f32_e32 v154, v71, v152
	v_sub_f32_e32 v0, v71, v154
	v_pk_fma_f32 v[232:233], v[232:233], s[22:23], v[154:155] op_sel:[0,1,0] op_sel_hi:[1,1,0] neg_lo:[0,0,1] neg_hi:[0,0,1]
	v_pk_fma_f32 v[234:235], v[234:235], s[22:23], v[154:155] op_sel:[0,1,0] op_sel_hi:[1,1,0] neg_lo:[0,0,1] neg_hi:[0,0,1]
	v_pk_fma_f32 v[236:237], v[236:237], s[22:23], v[154:155] op_sel:[0,1,0] op_sel_hi:[1,1,0] neg_lo:[0,0,1] neg_hi:[0,0,1]
	v_pk_fma_f32 v[238:239], v[238:239], s[22:23], v[154:155] op_sel:[0,1,0] op_sel_hi:[1,1,0] neg_lo:[0,0,1] neg_hi:[0,0,1]
	v_pk_fma_f32 v[240:241], v[240:241], s[22:23], v[154:155] op_sel:[0,1,0] op_sel_hi:[1,1,0] neg_lo:[0,0,1] neg_hi:[0,0,1]
	v_pk_fma_f32 v[242:243], v[242:243], s[22:23], v[154:155] op_sel:[0,1,0] op_sel_hi:[1,1,0] neg_lo:[0,0,1] neg_hi:[0,0,1]
	v_pk_fma_f32 v[244:245], v[244:245], s[22:23], v[154:155] op_sel:[0,1,0] op_sel_hi:[1,1,0] neg_lo:[0,0,1] neg_hi:[0,0,1]
	v_pk_fma_f32 v[246:247], v[246:247], s[22:23], v[154:155] op_sel:[0,1,0] op_sel_hi:[1,1,0] neg_lo:[0,0,1] neg_hi:[0,0,1]
	v_mfma_f32_32x32x16_bf16 v[34:49], v[184:187], v[58:61], v[34:49]
	v_exp_f32_e32 v0, v0
	v_exp_f32_e32 v232, v232
	v_exp_f32_e32 v233, v233
	v_exp_f32_e32 v234, v234
	v_exp_f32_e32 v235, v235
	v_exp_f32_e32 v236, v236
	v_exp_f32_e32 v237, v237
	v_exp_f32_e32 v238, v238
	v_mfma_f32_32x32x16_bf16 v[34:49], v[200:203], v[62:65], v[34:49]
	ds_read_b128 v[176:179], v248 offset:28672
	ds_read_b128 v[180:183], v249 offset:28672
	ds_read_b128 v[184:187], v250 offset:28672
	ds_read_b128 v[200:203], v251 offset:28672
	v_exp_f32_e32 v239, v239
	v_exp_f32_e32 v240, v240
	v_exp_f32_e32 v241, v241
	v_exp_f32_e32 v242, v242
	v_exp_f32_e32 v243, v243
	v_exp_f32_e32 v244, v244
	v_exp_f32_e32 v245, v245
	v_exp_f32_e32 v246, v246
	v_exp_f32_e32 v247, v247
	v_mov_b32_e32 v71, v154
	v_pk_add_f32 v[156:157], v[232:233], v[234:235]
	v_pk_add_f32 v[158:159], v[236:237], v[238:239]
	v_pk_add_f32 v[160:161], v[240:241], v[242:243]
	v_pk_add_f32 v[204:205], v[244:245], v[246:247]
	v_pk_add_f32 v[156:157], v[156:157], v[158:159]
	v_pk_add_f32 v[160:161], v[160:161], v[204:205]
	v_pk_add_f32 v[156:157], v[156:157], v[160:161]
	v_add_f32_e32 v206, v156, v157
	v_mov_b32_e32 v207, v206
	s_nop 1
	v_permlane32_swap_b32_e32 v206, v207
	v_cmp_neq_f32_e32 vcc, 1.0, v0
	s_cbranch_vccz .Lattn_qkeep_5
	v_pk_mul_f32 v[32:33], v[32:33], v[0:1] op_sel_hi:[1,0]
	v_pk_mul_f32 v[30:31], v[30:31], v[0:1] op_sel_hi:[1,0]
	v_pk_mul_f32 v[28:29], v[28:29], v[0:1] op_sel_hi:[1,0]
	v_pk_mul_f32 v[26:27], v[26:27], v[0:1] op_sel_hi:[1,0]
	v_pk_mul_f32 v[24:25], v[24:25], v[0:1] op_sel_hi:[1,0]
	v_pk_mul_f32 v[22:23], v[22:23], v[0:1] op_sel_hi:[1,0]
	v_pk_mul_f32 v[20:21], v[20:21], v[0:1] op_sel_hi:[1,0]
	v_pk_mul_f32 v[18:19], v[18:19], v[0:1] op_sel_hi:[1,0]
	v_pk_mul_f32 v[16:17], v[16:17], v[0:1] op_sel_hi:[1,0]
	v_pk_mul_f32 v[14:15], v[14:15], v[0:1] op_sel_hi:[1,0]
	v_pk_mul_f32 v[12:13], v[12:13], v[0:1] op_sel_hi:[1,0]
	v_pk_mul_f32 v[10:11], v[10:11], v[0:1] op_sel_hi:[1,0]
	v_pk_mul_f32 v[8:9], v[8:9], v[0:1] op_sel_hi:[1,0]
	v_pk_mul_f32 v[6:7], v[6:7], v[0:1] op_sel_hi:[1,0]
	v_pk_mul_f32 v[4:5], v[4:5], v[0:1] op_sel_hi:[1,0]
	v_pk_mul_f32 v[2:3], v[2:3], v[0:1] op_sel_hi:[1,0]
; DI unsigned pack2bf(float a, float b) { const f2_t v = {a, b}; return __builtin_bit_cast(unsigned, __builtin_convertvector(v, bf2_t)); }
; DI float xor32_max(float v) { const auto r = __builtin_amdgcn_permlane32_swap(__float_as_uint(v), __float_as_uint(v), false, false); return fmaxf(__uint_as_float(r[0]), __uint_as_float(r[1])); }
; DI int crow(int i, int hh) { return (i & 3) + 8 * (i >> 2) + 4 * hh; }
; DI void attn_task(const Params& P, int bh, int n, int t, int lane, const char* Ks, const char* Vs) {
;     ...
;     for (int s = 0; s < 4; ++s) {
;       const bf16x8 kf = *reinterpret_cast<const bf16x8*>(Ks + krow * 128 + (((2 * s + hh) ^ ((krow >> 1) & 7)) * 16));
;       S = __builtin_amdgcn_mfma_f32_32x32x16_bf16(kf, qf[s], S, 0, 0, 0);
;     }
;     const bool diag = own && (kt == t);
;     constexpr float SC2 = 0.125f * 1.4426950408889634f;
;     float mx = -1e30f;
; #pragma unroll
;     for (int i = 0; i < 16; ++i) {
;       if (diag && (kbase + crow(i, hh) > lq)) S[i] = -1e30f;
;       mx = fmaxf(mx, S[i]);
;     }
;     mx = xor32_max(mx);
;     const float m_new = fmaxf(m_run, mx * SC2);
;     const float alpha = __builtin_amdgcn_exp2f(m_run - m_new);
;     float rs = 0.f;
; #pragma unroll
;     for (int i = 0; i < 16; ++i) { float pv = __builtin_amdgcn_exp2f(fmaf(S[i], SC2, -m_new)); S[i] = pv; rs += pv; }
;     rs = xor32_sum(rs);
;     l_run = l_run * alpha + rs; m_run = m_new;
;     if (__ballot(alpha != 1.f)) {
; #pragma unroll
;       for (int i = 0; i < 16; ++i) { O0[i] *= alpha; O1[i] *= alpha; }
;     }
; #pragma unroll
;     for (int s = 0; s < 2; ++s) {
;       const uint4 ppk = make_uint4(pack2bf(S[8 * s], S[8 * s + 1]), pack2bf(S[8 * s + 2], S[8 * s + 3]), pack2bf(S[8 * s + 4], S[8 * s + 5]), pack2bf(S[8 * s + 6], S[8 * s + 7]));
;       const bf16x8 pf = __builtin_bit_cast(bf16x8, ppk);
; #pragma unroll
;       for (int dt = 0; dt < 2; ++dt) {
;         const char* vp = Vs + (dt * 32 + r) * 528 + (kt * 32 + 16 * s + 4 * hh) * 2;
;         const uint2 lo = *reinterpret_cast<const uint2*>(vp), hi = *reinterpret_cast<const uint2*>(vp + 16);
;         const uint4 vv = make_uint4(lo.x, lo.y, hi.x, hi.y);
;         if (dt == 0) O0 = __builtin_amdgcn_mfma_f32_32x32x16_bf16(__builtin_bit_cast(bf16x8, vv), pf, O0, 0, 0, 0);
;         else O1 = __builtin_amdgcn_mfma_f32_32x32x16_bf16(__builtin_bit_cast(bf16x8, vv), pf, O1, 0, 0, 0);
;       }
.Lattn_qkeep_5:
	v_add_f32_e32 v252, v206, v207
	v_fmac_f32_e32 v252, v151, v0
	v_cvt_pk_bf16_f32 v156, v232, v233
	v_cvt_pk_bf16_f32 v157, v234, v235
	v_cvt_pk_bf16_f32 v158, v236, v237
	v_cvt_pk_bf16_f32 v159, v238, v239
	v_cvt_pk_bf16_f32 v152, v240, v241
	v_cvt_pk_bf16_f32 v153, v242, v243
	v_cvt_pk_bf16_f32 v154, v244, v245
	v_cvt_pk_bf16_f32 v155, v246, v247
	v_mov_b32_e32 v151, v252
	s_waitcnt lgkmcnt(0)
	v_mfma_f32_32x32x16_bf16 v[18:33], v[216:219], v[156:159], v[18:33]
	v_mfma_f32_32x32x16_bf16 v[2:17], v[220:223], v[156:159], v[2:17]
	v_mfma_f32_32x32x16_bf16 v[18:33], v[224:227], v[152:155], v[18:33]
	v_mfma_f32_32x32x16_bf16 v[2:17], v[228:231], v[152:155], v[2:17]
	s_waitcnt lgkmcnt(0)
	v_mfma_f32_32x32x16_bf16 v[232:247], v[176:179], v[50:53], 0
	ds_read2_b64 v[216:219], v210 offset0:48 offset1:50
	ds_read2_b64 v[220:223], v211 offset0:48 offset1:50
	ds_read2_b64 v[224:227], v210 offset0:52 offset1:54
	ds_read2_b64 v[228:231], v211 offset0:52 offset1:54
	v_max3_f32 v152, v34, s22, v35
	v_max3_f32 v152, v152, v36, v37
	v_max3_f32 v152, v152, v38, v39
	v_max3_f32 v152, v152, v40, v41
	v_max3_f32 v152, v152, v42, v43
	v_max3_f32 v152, v152, v44, v45
	v_max3_f32 v152, v152, v46, v47
	v_max3_f32 v152, v152, v48, v49
	v_mfma_f32_32x32x16_bf16 v[232:247], v[180:183], v[54:57], v[232:247]
	v_mov_b32_e32 v153, v152
	s_nop 1
	v_permlane32_swap_b32_e32 v152, v153
	v_max_f32_e32 v152, v152, v153
	v_mul_f32_e32 v152, 0x3e38aa3b, v152
	v_max_f32_e32 v154, v71, v152
	v_sub_f32_e32 v0, v71, v154
	v_pk_fma_f32 v[34:35], v[34:35], s[22:23], v[154:155] op_sel:[0,1,0] op_sel_hi:[1,1,0] neg_lo:[0,0,1] neg_hi:[0,0,1]
	v_pk_fma_f32 v[36:37], v[36:37], s[22:23], v[154:155] op_sel:[0,1,0] op_sel_hi:[1,1,0] neg_lo:[0,0,1] neg_hi:[0,0,1]
	v_pk_fma_f32 v[38:39], v[38:39], s[22:23], v[154:155] op_sel:[0,1,0] op_sel_hi:[1,1,0] neg_lo:[0,0,1] neg_hi:[0,0,1]
	v_pk_fma_f32 v[40:41], v[40:41], s[22:23], v[154:155] op_sel:[0,1,0] op_sel_hi:[1,1,0] neg_lo:[0,0,1] neg_hi:[0,0,1]
	v_pk_fma_f32 v[42:43], v[42:43], s[22:23], v[154:155] op_sel:[0,1,0] op_sel_hi:[1,1,0] neg_lo:[0,0,1] neg_hi:[0,0,1]
	v_pk_fma_f32 v[44:45], v[44:45], s[22:23], v[154:155] op_sel:[0,1,0] op_sel_hi:[1,1,0] neg_lo:[0,0,1] neg_hi:[0,0,1]
	v_pk_fma_f32 v[46:47], v[46:47], s[22:23], v[154:155] op_sel:[0,1,0] op_sel_hi:[1,1,0] neg_lo:[0,0,1] neg_hi:[0,0,1]
	v_pk_fma_f32 v[48:49], v[48:49], s[22:23], v[154:155] op_sel:[0,1,0] op_sel_hi:[1,1,0] neg_lo:[0,0,1] neg_hi:[0,0,1]
	v_mfma_f32_32x32x16_bf16 v[232:247], v[184:187], v[58:61], v[232:247]
	v_exp_f32_e32 v0, v0
	v_exp_f32_e32 v34, v34
	v_exp_f32_e32 v35, v35
	v_exp_f32_e32 v36, v36
	v_exp_f32_e32 v37, v37
	v_exp_f32_e32 v38, v38
	v_exp_f32_e32 v39, v39
	v_exp_f32_e32 v40, v40
	v_mfma_f32_32x32x16_bf16 v[232:247], v[200:203], v[62:65], v[232:247]
	v_exp_f32_e32 v41, v41
	v_exp_f32_e32 v42, v42
	v_exp_f32_e32 v43, v43
	v_exp_f32_e32 v44, v44
	v_exp_f32_e32 v45, v45
	v_exp_f32_e32 v46, v46
	v_exp_f32_e32 v47, v47
	v_exp_f32_e32 v48, v48
	v_exp_f32_e32 v49, v49
	v_mov_b32_e32 v71, v154
	v_pk_add_f32 v[156:157], v[34:35], v[36:37]
	v_pk_add_f32 v[158:159], v[38:39], v[40:41]
	v_pk_add_f32 v[160:161], v[42:43], v[44:45]
	v_pk_add_f32 v[204:205], v[46:47], v[48:49]
	v_pk_add_f32 v[156:157], v[156:157], v[158:159]
	v_pk_add_f32 v[160:161], v[160:161], v[204:205]
	v_pk_add_f32 v[156:157], v[156:157], v[160:161]
	v_add_f32_e32 v206, v156, v157
	v_mov_b32_e32 v207, v206
	s_nop 1
	v_permlane32_swap_b32_e32 v206, v207
	v_cmp_neq_f32_e32 vcc, 1.0, v0
	s_cbranch_vccz .Lattn_qkeep_6
	v_pk_mul_f32 v[32:33], v[32:33], v[0:1] op_sel_hi:[1,0]
	v_pk_mul_f32 v[30:31], v[30:31], v[0:1] op_sel_hi:[1,0]
	v_pk_mul_f32 v[28:29], v[28:29], v[0:1] op_sel_hi:[1,0]
	v_pk_mul_f32 v[26:27], v[26:27], v[0:1] op_sel_hi:[1,0]
	v_pk_mul_f32 v[24:25], v[24:25], v[0:1] op_sel_hi:[1,0]
	v_pk_mul_f32 v[22:23], v[22:23], v[0:1] op_sel_hi:[1,0]
	v_pk_mul_f32 v[20:21], v[20:21], v[0:1] op_sel_hi:[1,0]
	v_pk_mul_f32 v[18:19], v[18:19], v[0:1] op_sel_hi:[1,0]
	v_pk_mul_f32 v[16:17], v[16:17], v[0:1] op_sel_hi:[1,0]
	v_pk_mul_f32 v[14:15], v[14:15], v[0:1] op_sel_hi:[1,0]
	v_pk_mul_f32 v[12:13], v[12:13], v[0:1] op_sel_hi:[1,0]
	v_pk_mul_f32 v[10:11], v[10:11], v[0:1] op_sel_hi:[1,0]
	v_pk_mul_f32 v[8:9], v[8:9], v[0:1] op_sel_hi:[1,0]
	v_pk_mul_f32 v[6:7], v[6:7], v[0:1] op_sel_hi:[1,0]
	v_pk_mul_f32 v[4:5], v[4:5], v[0:1] op_sel_hi:[1,0]
	v_pk_mul_f32 v[2:3], v[2:3], v[0:1] op_sel_hi:[1,0]
; DI unsigned pack2bf(float a, float b) { const f2_t v = {a, b}; return __builtin_bit_cast(unsigned, __builtin_convertvector(v, bf2_t)); }
; DI float xor32_max(float v) { const auto r = __builtin_amdgcn_permlane32_swap(__float_as_uint(v), __float_as_uint(v), false, false); return fmaxf(__uint_as_float(r[0]), __uint_as_float(r[1])); }
; DI float xor32_sum(float v) { const auto r = __builtin_amdgcn_permlane32_swap(__float_as_uint(v), __float_as_uint(v), false, false); return __uint_as_float(r[0]) + __uint_as_float(r[1]); }
; DI int crow(int i, int hh) { return (i & 3) + 8 * (i >> 2) + 4 * hh; }
; DI void attn_task(const Params& P, int bh, int n, int t, int lane, const char* Ks, const char* Vs) {
;     ...
;     for (int i = 0; i < 16; ++i) {
;       if (diag && (kbase + crow(i, hh) > lq)) S[i] = -1e30f;
;       mx = fmaxf(mx, S[i]);
;     }
;     mx = xor32_max(mx);
;     const float m_new = fmaxf(m_run, mx * SC2);
;     const float alpha = __builtin_amdgcn_exp2f(m_run - m_new);
;     float rs = 0.f;
; #pragma unroll
;     for (int i = 0; i < 16; ++i) { float pv = __builtin_amdgcn_exp2f(fmaf(S[i], SC2, -m_new)); S[i] = pv; rs += pv; }
;     rs = xor32_sum(rs);
;     l_run = l_run * alpha + rs; m_run = m_new;
;     if (__ballot(alpha != 1.f)) {
; #pragma unroll
;       for (int i = 0; i < 16; ++i) { O0[i] *= alpha; O1[i] *= alpha; }
;     }
; #pragma unroll
;     for (int s = 0; s < 2; ++s) {
;       const uint4 ppk = make_uint4(pack2bf(S[8 * s], S[8 * s + 1]), pack2bf(S[8 * s + 2], S[8 * s + 3]), pack2bf(S[8 * s + 4], S[8 * s + 5]), pack2bf(S[8 * s + 6], S[8 * s + 7]));
;       const bf16x8 pf = __builtin_bit_cast(bf16x8, ppk);
; #pragma unroll
;       for (int dt = 0; dt < 2; ++dt) {
;         const char* vp = Vs + (dt * 32 + r) * 528 + (kt * 32 + 16 * s + 4 * hh) * 2;
;         const uint2 lo = *reinterpret_cast<const uint2*>(vp), hi = *reinterpret_cast<const uint2*>(vp + 16);
;         const uint4 vv = make_uint4(lo.x, lo.y, hi.x, hi.y);
;         if (dt == 0) O0 = __builtin_amdgcn_mfma_f32_32x32x16_bf16(__builtin_bit_cast(bf16x8, vv), pf, O0, 0, 0, 0);
;         else O1 = __builtin_amdgcn_mfma_f32_32x32x16_bf16(__builtin_bit_cast(bf16x8, vv), pf, O1, 0, 0, 0);
;       }
;     }
;   }
.Lattn_qkeep_6:
	v_add_f32_e32 v252, v206, v207
	v_fmac_f32_e32 v252, v151, v0
	v_cvt_pk_bf16_f32 v156, v34, v35
	v_cvt_pk_bf16_f32 v157, v36, v37
	v_cvt_pk_bf16_f32 v158, v38, v39
	v_cvt_pk_bf16_f32 v159, v40, v41
	v_cvt_pk_bf16_f32 v152, v42, v43
	v_cvt_pk_bf16_f32 v153, v44, v45
	v_cvt_pk_bf16_f32 v154, v46, v47
	v_cvt_pk_bf16_f32 v155, v48, v49
	v_mov_b32_e32 v151, v252
	s_waitcnt lgkmcnt(0)
	v_mfma_f32_32x32x16_bf16 v[18:33], v[216:219], v[156:159], v[18:33]
	v_mfma_f32_32x32x16_bf16 v[2:17], v[220:223], v[156:159], v[2:17]
	v_mfma_f32_32x32x16_bf16 v[18:33], v[224:227], v[152:155], v[18:33]
	v_mfma_f32_32x32x16_bf16 v[2:17], v[228:231], v[152:155], v[2:17]
	s_waitcnt lgkmcnt(0)
	v_max3_f32 v152, v232, s22, v233
	v_max3_f32 v152, v152, v234, v235
	v_max3_f32 v152, v152, v236, v237
	v_max3_f32 v152, v152, v238, v239
	v_max3_f32 v152, v152, v240, v241
	v_max3_f32 v152, v152, v242, v243
	v_max3_f32 v152, v152, v244, v245
	v_max3_f32 v152, v152, v246, v247
	ds_read2_b64 v[216:219], v210 offset0:56 offset1:58
	ds_read2_b64 v[220:223], v211 offset0:56 offset1:58
	ds_read2_b64 v[224:227], v210 offset0:60 offset1:62
	ds_read2_b64 v[228:231], v211 offset0:60 offset1:62
	v_mov_b32_e32 v153, v152
	s_nop 1
	v_permlane32_swap_b32_e32 v152, v153
	v_max_f32_e32 v152, v152, v153
	v_mul_f32_e32 v152, 0x3e38aa3b, v152
	v_max_f32_e32 v154, v71, v152
	v_sub_f32_e32 v0, v71, v154
	v_pk_fma_f32 v[232:233], v[232:233], s[22:23], v[154:155] op_sel:[0,1,0] op_sel_hi:[1,1,0] neg_lo:[0,0,1] neg_hi:[0,0,1]
	v_pk_fma_f32 v[234:235], v[234:235], s[22:23], v[154:155] op_sel:[0,1,0] op_sel_hi:[1,1,0] neg_lo:[0,0,1] neg_hi:[0,0,1]
	v_pk_fma_f32 v[236:237], v[236:237], s[22:23], v[154:155] op_sel:[0,1,0] op_sel_hi:[1,1,0] neg_lo:[0,0,1] neg_hi:[0,0,1]
	v_pk_fma_f32 v[238:239], v[238:239], s[22:23], v[154:155] op_sel:[0,1,0] op_sel_hi:[1,1,0] neg_lo:[0,0,1] neg_hi:[0,0,1]
	v_pk_fma_f32 v[240:241], v[240:241], s[22:23], v[154:155] op_sel:[0,1,0] op_sel_hi:[1,1,0] neg_lo:[0,0,1] neg_hi:[0,0,1]
	v_pk_fma_f32 v[242:243], v[242:243], s[22:23], v[154:155] op_sel:[0,1,0] op_sel_hi:[1,1,0] neg_lo:[0,0,1] neg_hi:[0,0,1]
	v_pk_fma_f32 v[244:245], v[244:245], s[22:23], v[154:155] op_sel:[0,1,0] op_sel_hi:[1,1,0] neg_lo:[0,0,1] neg_hi:[0,0,1]
	v_pk_fma_f32 v[246:247], v[246:247], s[22:23], v[154:155] op_sel:[0,1,0] op_sel_hi:[1,1,0] neg_lo:[0,0,1] neg_hi:[0,0,1]
	v_exp_f32_e32 v0, v0
	v_exp_f32_e32 v232, v232
	v_exp_f32_e32 v233, v233
	v_exp_f32_e32 v234, v234
	v_exp_f32_e32 v235, v235
	v_exp_f32_e32 v236, v236
	v_exp_f32_e32 v237, v237
	v_exp_f32_e32 v238, v238
	v_exp_f32_e32 v239, v239
	v_exp_f32_e32 v240, v240
	v_exp_f32_e32 v241, v241
	v_exp_f32_e32 v242, v242
	v_exp_f32_e32 v243, v243
	v_exp_f32_e32 v244, v244
	v_exp_f32_e32 v245, v245
	v_exp_f32_e32 v246, v246
	v_exp_f32_e32 v247, v247
	v_mov_b32_e32 v71, v154
	v_pk_add_f32 v[156:157], v[232:233], v[234:235]
	v_pk_add_f32 v[158:159], v[236:237], v[238:239]
	v_pk_add_f32 v[160:161], v[240:241], v[242:243]
	v_pk_add_f32 v[204:205], v[244:245], v[246:247]
	v_pk_add_f32 v[156:157], v[156:157], v[158:159]
	v_pk_add_f32 v[160:161], v[160:161], v[204:205]
	v_pk_add_f32 v[156:157], v[156:157], v[160:161]
	v_add_f32_e32 v206, v156, v157
	v_mov_b32_e32 v207, v206
	s_nop 1
	v_permlane32_swap_b32_e32 v206, v207
	v_cmp_neq_f32_e32 vcc, 1.0, v0
	s_cbranch_vccz .Lattn_qkeep_7
	v_pk_mul_f32 v[32:33], v[32:33], v[0:1] op_sel_hi:[1,0]
	v_pk_mul_f32 v[30:31], v[30:31], v[0:1] op_sel_hi:[1,0]
	v_pk_mul_f32 v[28:29], v[28:29], v[0:1] op_sel_hi:[1,0]
	v_pk_mul_f32 v[26:27], v[26:27], v[0:1] op_sel_hi:[1,0]
	v_pk_mul_f32 v[24:25], v[24:25], v[0:1] op_sel_hi:[1,0]
	v_pk_mul_f32 v[22:23], v[22:23], v[0:1] op_sel_hi:[1,0]
	v_pk_mul_f32 v[20:21], v[20:21], v[0:1] op_sel_hi:[1,0]
	v_pk_mul_f32 v[18:19], v[18:19], v[0:1] op_sel_hi:[1,0]
	v_pk_mul_f32 v[16:17], v[16:17], v[0:1] op_sel_hi:[1,0]
	v_pk_mul_f32 v[14:15], v[14:15], v[0:1] op_sel_hi:[1,0]
	v_pk_mul_f32 v[12:13], v[12:13], v[0:1] op_sel_hi:[1,0]
	v_pk_mul_f32 v[10:11], v[10:11], v[0:1] op_sel_hi:[1,0]
	v_pk_mul_f32 v[8:9], v[8:9], v[0:1] op_sel_hi:[1,0]
	v_pk_mul_f32 v[6:7], v[6:7], v[0:1] op_sel_hi:[1,0]
	v_pk_mul_f32 v[4:5], v[4:5], v[0:1] op_sel_hi:[1,0]
	v_pk_mul_f32 v[2:3], v[2:3], v[0:1] op_sel_hi:[1,0]
.Lattn_qkeep_7:
	v_add_f32_e32 v252, v206, v207
	v_fmac_f32_e32 v252, v151, v0
	v_cvt_pk_bf16_f32 v156, v232, v233
	v_cvt_pk_bf16_f32 v157, v234, v235
	v_cvt_pk_bf16_f32 v158, v236, v237
	v_cvt_pk_bf16_f32 v159, v238, v239
	v_cvt_pk_bf16_f32 v152, v240, v241
	v_cvt_pk_bf16_f32 v153, v242, v243
	v_cvt_pk_bf16_f32 v154, v244, v245
	v_cvt_pk_bf16_f32 v155, v246, v247
	v_mov_b32_e32 v151, v252
	s_waitcnt lgkmcnt(0)
	v_mfma_f32_32x32x16_bf16 v[18:33], v[216:219], v[156:159], v[18:33]
	v_mfma_f32_32x32x16_bf16 v[2:17], v[220:223], v[156:159], v[2:17]
	v_mfma_f32_32x32x16_bf16 v[18:33], v[224:227], v[152:155], v[18:33]
	v_mfma_f32_32x32x16_bf16 v[2:17], v[228:231], v[152:155], v[2:17]
	v_mov_b32_e32 v36, v151
	s_branch .LBB0_798
